# v48 + mLSTM piece 2 state-update: remaining nine LDS operand reads issued up front into spare VGPRs
# baseline (speedup 1.0000x reference)
; #define LAS __attribute__((address_space(3)))
; __device__ __forceinline__ f32x4 mfma16(bf16x8 a, bf16x8 b, f32x4 c) { return __builtin_amdgcn_mfma_f32_16x16x32_bf16(a, b, c, 0, 0, 0); }
; __device__ __forceinline__ void lds_barrier() { asm volatile("s_waitcnt lgkmcnt(0)" ::: "memory"); __builtin_amdgcn_s_barrier(); asm volatile("" ::: "memory"); }
; __device__ __forceinline__ void mlstm_item(const P& p, const Ctx& c, int seg, int w, bool save) {
;     ...
;         const float gtot = gtotp[0];
; #pragma unroll
;         for (int j = 0; j < 12; ++j) C[j] *= gtot;
;         f32x4 Sa[2], Ia[2]; Sa[0] = Sa[1] = Ia[0] = Ia[1] = (f32x4){0.f, 0.f, 0.f, 0.f};
;         float qnacc = 0.f;
; #pragma unroll
;         for (int pp = 0; pp < 3; ++pp) {
;             const int d0 = pp * 128;
;             __builtin_amdgcn_sched_barrier(0);
;             asm volatile("" : "+v"(tidv));
;             lds_barrier();
; #pragma unroll
;             for (int r = 0; r < 2; ++r) { const int id = tidv + 512 * r;
;                 { const int i = id >> 4, c8 = (id & 15) * 8; *(LAS u32x4*)(Qs + i * 136 + c8) = pq[r]; *(LAS u32x4*)(Ks + i * 136 + c8) = pk[r]; }
;                 { const int dd = id >> 3, c8 = (id & 7) * 8; *(LAS u32x4*)(KTs + dd * 72 + c8) = pt[r]; } }
;             lds_barrier();
;             if (pp < 2) gl_piece(ch, pp + 1, tidv); else if (ch + 1 < 8) gl_piece(ch + 1, 0, tidv);
;             { const int tm = c.wv >> 1, tn0 = (c.wv & 1) * 2;
; #pragma unroll
;               for (int kk = 0; kk < 4; ++kk) { const bf16x8 a = *(const LAS bf16x8*)(Qs + (tm * 16 + l15) * 136 + kk * 32 + quad * 8);
; #pragma unroll
;                   for (int x = 0; x < 2; ++x) { const int tn = tn0 + x;
;                       const bf16x8 bk = *(const LAS bf16x8*)(Ks + (tn * 16 + l15) * 136 + kk * 32 + quad * 8);
;                       const bf16x8 bc = *(const LAS bf16x8*)(Cimg + (tn * 16 + l15) * 392 + d0 + kk * 32 + quad * 8);
;                       Sa[x] = mfma16(a, bk, Sa[x]); Ia[x] = mfma16(a, bc, Ia[x]); } } }
.LBB0_375:
	s_or_b64 exec, exec, s[92:93]
	v_mov_b32_e32 v183, v182
	v_mov_b32_e32 v122, v182
	v_mov_b32_e32 v123, v182
	v_pk_mul_f32 v[12:13], v[12:13], v[122:123]
	v_pk_mul_f32 v[10:11], v[10:11], v[182:183]
	v_pk_mul_f32 v[20:21], v[20:21], v[122:123]
	v_pk_mul_f32 v[18:19], v[18:19], v[182:183]
	v_pk_mul_f32 v[32:33], v[32:33], v[122:123]
	v_pk_mul_f32 v[30:31], v[30:31], v[182:183]
	v_pk_mul_f32 v[36:37], v[36:37], v[122:123]
	v_pk_mul_f32 v[34:35], v[34:35], v[182:183]
	s_waitcnt lgkmcnt(0)
	s_barrier
	v_lshlrev_b32_e32 v4, 3, v191
	v_and_b32_e32 v128, 0x78, v4
	v_lshlrev_b32_e32 v4, 1, v128
	v_ashrrev_i32_e32 v126, 4, v191
	v_add_u32_e32 v122, 0, v4
	v_add_u32_e32 v123, s50, v4
	v_lshlrev_b32_e32 v4, 4, v191
	v_mul_lo_u32 v124, v126, s38
	v_and_b32_e32 v159, 0x70, v4
	v_add_u32_e32 v125, v122, v124
	v_add_u32_e32 v4, s18, v159
	s_waitcnt vmcnt(5)
	ds_write_b128 v125, v[78:81] offset:50176
	v_add_u32_e32 v78, v123, v124
	v_ashrrev_i32_e32 v146, 3, v191
	s_waitcnt vmcnt(4)
	ds_write_b128 v78, v[74:77]
	v_mad_u64_u32 v[74:75], s[92:93], v146, s63, v[4:5]
	s_waitcnt vmcnt(3)
	ds_write_b128 v74, v[106:109]
	v_add_u32_e32 v74, 0x200, v191
	v_ashrrev_i32_e32 v148, 4, v74
	v_mul_lo_u32 v75, v148, s38
	v_add_u32_e32 v76, v122, v75
	v_add_u32_e32 v75, v123, v75
	v_ashrrev_i32_e32 v150, 3, v74
	s_waitcnt vmcnt(1)
	ds_write_b128 v75, v[110:113]
	v_mad_u64_u32 v[74:75], s[92:93], v150, s63, v[4:5]
	ds_write_b128 v76, v[114:117] offset:50176
	s_waitcnt vmcnt(0)
	ds_write_b128 v74, v[118:121]
	s_waitcnt lgkmcnt(0)
	s_barrier
	ds_read_b128 v[74:77], v157 offset:50176
	ds_read_b128 v[78:81], v158
	ds_read_b128 v[106:109], v157 offset:50240
	ds_read_b128 v[110:113], v158 offset:64
	s_waitcnt lgkmcnt(2)
	v_mfma_f32_16x16x32_bf16 v[62:65], v[74:77], v[78:81], v[62:65]
	ds_read_b128 v[78:81], v155 offset:256
	ds_read_b128 v[114:117], v155 offset:320
	v_ashrrev_i32_e32 v127, 31, v126
	v_or_b32_e32 v4, s47, v128
	s_waitcnt lgkmcnt(1)
	v_mfma_f32_16x16x32_bf16 v[70:73], v[74:77], v[78:81], v[70:73]
	ds_read_b128 v[78:81], v156
	ds_read_b128 v[118:121], v156 offset:64
	ds_read_b128 v[122:125], v153 offset:320
	v_ashrrev_i32_e32 v147, 31, v146
	s_waitcnt lgkmcnt(2)
	v_mfma_f32_16x16x32_bf16 v[66:69], v[74:77], v[78:81], v[66:69]
	ds_read_b128 v[78:81], v153 offset:256
	s_mov_b32 s41, 0xff440000
	v_ashrrev_i32_e32 v149, 31, v148
	s_waitcnt lgkmcnt(0)
	v_mfma_f32_16x16x32_bf16 v[58:61], v[74:77], v[78:81], v[58:61]
	v_lshl_add_u64 v[74:75], s[86:87], 0, v[126:127]
	v_lshl_add_u64 v[74:75], v[74:75], 0, s[60:61]
	v_mad_u64_u32 v[78:79], s[92:93], v74, s58, v[4:5]
	v_mov_b32_e32 v74, v79
	v_mad_u64_u32 v[80:81], s[92:93], v75, s58, v[74:75]
	ds_read_b128 v[74:77], v157 offset:50304
	v_mov_b32_e32 v79, v80
	v_lshlrev_b64 v[126:127], 1, v[78:79]
	ds_read_b128 v[78:81], v158 offset:128
	v_mfma_f32_16x16x32_bf16 v[62:65], v[106:109], v[110:113], v[62:65]
	v_lshl_add_u64 v[130:131], s[72:73], 0, v[126:127]
	v_lshl_add_u64 v[132:133], s[74:75], 0, v[126:127]
	v_ashrrev_i32_e32 v151, 31, v150
	v_mfma_f32_16x16x32_bf16 v[70:73], v[106:109], v[114:117], v[70:73]
	v_mfma_f32_16x16x32_bf16 v[66:69], v[106:109], v[118:121], v[66:69]
	v_mfma_f32_16x16x32_bf16 v[106:109], v[106:109], v[122:125], v[58:61]
	s_nop 2
	ds_read_b128 v[58:61], v155 offset:384
	ds_read_b128 v[110:113], v157 offset:50368
	ds_read_b128 v[114:117], v158 offset:192
	s_waitcnt lgkmcnt(3)
	v_mfma_f32_16x16x32_bf16 v[78:81], v[74:77], v[78:81], v[62:65]
	s_nop 2
	ds_read_b128 v[62:65], v156 offset:128
	ds_read_b128 v[118:121], v155 offset:448
	ds_read_b128 v[122:125], v153 offset:384
	ds_read_b128 v[126:129], v156 offset:192
	s_waitcnt lgkmcnt(6)
	v_mfma_f32_16x16x32_bf16 v[70:73], v[74:77], v[58:61], v[70:73]
	s_waitcnt lgkmcnt(3)
	v_mfma_f32_16x16x32_bf16 v[138:141], v[74:77], v[62:65], v[66:69]
	global_load_dwordx4 v[58:61], v[130:131], off
	global_load_dwordx4 v[62:65], v[132:133], off
	ds_read_b128 v[142:145], v153 offset:448
	v_lshlrev_b64 v[66:67], 10, v[146:147]
	s_waitcnt lgkmcnt(2)
	v_mfma_f32_16x16x32_bf16 v[74:77], v[74:77], v[122:125], v[106:109]
	v_or_b32_e32 v66, v66, v159
	v_lshl_add_u64 v[66:67], s[16:17], 0, v[66:67]
	v_add_co_u32_e32 v66, vcc, s41, v66
	ds_read_b128 v[106:109], v152
	s_nop 0
	v_addc_co_u32_e32 v67, vcc, -1, v67, vcc
	v_mfma_f32_16x16x32_bf16 v[134:137], v[110:113], v[118:121], v[70:73]
	global_load_dwordx4 v[66:69], v[66:67], off offset:-128
	s_nop 1
	v_lshl_add_u64 v[70:71], s[86:87], 0, v[148:149]
	v_mfma_f32_16x16x32_bf16 v[130:133], v[110:113], v[114:117], v[78:81]
	s_nop 2
	v_lshl_add_u64 v[78:79], v[70:71], 0, s[60:61]
	s_waitcnt lgkmcnt(2)
; #define LAS __attribute__((address_space(3)))
; __device__ __forceinline__ void mlstm_item(const P& p, const Ctx& c, int seg, int w, bool save) {
;     ...
;             { const bf16x8 va0 = *(const LAS bf16x8*)(VWs + (e16 * 16 + l15) * 72 + quad * 8), va1 = *(const LAS bf16x8*)(VWs + (e16 * 16 + l15) * 72 + 32 + quad * 8);
; #pragma unroll
;               for (int jl = 0; jl < 4; ++jl) { const int ntl = 2 * jl + par, j = pp * 4 + jl;
;                   C[j] = mfma16(va0, *(const LAS bf16x8*)(KTs + (ntl * 16 + l15) * 72 + quad * 8), C[j]);
;                   C[j] = mfma16(va1, *(const LAS bf16x8*)(KTs + (ntl * 16 + l15) * 72 + 32 + quad * 8), C[j]); } }
;             { const int t = tidv >> 3, part = tidv & 7;
;               const u32x4 q0 = *(const LAS u32x4*)(Qs + t * 136 + part * 16), q1 = *(const LAS u32x4*)(Qs + t * 136 + part * 16 + 8);
;               const LAS float* np = nold + d0 + part * 16; const f32x4 n0 = *(const LAS f32x4*)np, n1 = *(const LAS f32x4*)(np + 4), n2 = *(const LAS f32x4*)(np + 8), n3 = *(const LAS f32x4*)(np + 12);
;               qnacc += bflo(q0.x) * n0[0] + bfhi(q0.x) * n0[1] + bflo(q0.y) * n0[2] + bfhi(q0.y) * n0[3] + bflo(q0.z) * n1[0] + bfhi(q0.z) * n1[1] + bflo(q0.w) * n1[2] + bfhi(q0.w) * n1[3]
;                      + bflo(q1.x) * n2[0] + bfhi(q1.x) * n2[1] + bflo(q1.y) * n2[2] + bfhi(q1.y) * n2[3] + bflo(q1.z) * n3[0] + bfhi(q1.z) * n3[1] + bflo(q1.w) * n3[2] + bfhi(q1.w) * n3[3]; }
;             { const int dd = tidv >> 2, part = tidv & 3;
;               const u32x4 k0 = *(const LAS u32x4*)(KTs + dd * 72 + part * 16), k1 = *(const LAS u32x4*)(KTs + dd * 72 + part * 16 + 8);
;               const LAS float* wp = wgt + part * 16; const f32x4 w0 = *(const LAS f32x4*)wp, w1 = *(const LAS f32x4*)(wp + 4), w2 = *(const LAS f32x4*)(wp + 8), w3 = *(const LAS f32x4*)(wp + 12);
;               float a = bflo(k0.x) * w0[0] + bfhi(k0.x) * w0[1] + bflo(k0.y) * w0[2] + bfhi(k0.y) * w0[3] + bflo(k0.z) * w1[0] + bfhi(k0.z) * w1[1] + bflo(k0.w) * w1[2] + bfhi(k0.w) * w1[3]
;                       + bflo(k1.x) * w2[0] + bfhi(k1.x) * w2[1] + bflo(k1.y) * w2[2] + bfhi(k1.y) * w2[3] + bflo(k1.z) * w3[0] + bfhi(k1.z) * w3[1] + bflo(k1.w) * w3[2] + bfhi(k1.w) * w3[3];
;               a = dpp_add<0xB1>(a); a = dpp_add<0x4E>(a);
;               if (part == 0) nnew[d0 + dd] = gtot * nold[d0 + dd] + a; }
	v_mfma_f32_16x16x32_bf16 v[138:141], v[110:113], v[126:129], v[138:141]
	v_mad_u64_u32 v[80:81], s[92:93], v78, s58, v[4:5]
	v_mov_b32_e32 v4, v81
	s_waitcnt lgkmcnt(1)
	v_mfma_f32_16x16x32_bf16 v[142:145], v[110:113], v[142:145], v[74:77]
	ds_read_b128 v[110:113], v152 offset:64
	ds_read_b128 v[208:211], v154
	ds_read_b128 v[218:221], v154 offset:4608
	ds_read_b128 v[234:237], v154 offset:64
	ds_read_b128 v[238:241], v154 offset:4672
	ds_read_b128 v[242:245], v154 offset:9216
	ds_read_b128 v[246:249], v154 offset:13824
	ds_read_b128 v[250:253], v154 offset:9280
	v_mad_u64_u32 v[74:75], s[92:93], v79, s58, v[4:5]
	v_mov_b32_e32 v81, v74
	v_lshlrev_b64 v[70:71], 1, v[80:81]
	v_lshl_add_u64 v[72:73], s[72:73], 0, v[70:71]
	v_lshlrev_b64 v[78:79], 10, v[150:151]
	v_lshl_add_u64 v[114:115], s[74:75], 0, v[70:71]
	v_or_b32_e32 v78, v78, v159
	global_load_dwordx4 v[70:73], v[72:73], off
	s_nop 0
	global_load_dwordx4 v[74:77], v[114:115], off
	ds_read_b128 v[114:117], v154 offset:13888
	v_lshl_add_u64 v[118:119], s[16:17], 0, v[78:79]
	v_add_co_u32_e32 v118, vcc, s41, v118
	s_nop 1
	v_addc_co_u32_e32 v119, vcc, -1, v119, vcc
	global_load_dwordx4 v[78:81], v[118:119], off offset:-128
	v_mul_lo_u32 v4, v146, s38
	v_and_b32_e32 v150, 3, v191
	v_lshlrev_b32_e32 v147, 5, v150
	v_cmp_eq_u32_e32 vcc, 0, v150
	s_waitcnt lgkmcnt(7)
	v_mfma_f32_16x16x32_bf16 v[10:13], v[106:109], v[208:211], v[10:13]
	s_waitcnt lgkmcnt(6)
	v_mfma_f32_16x16x32_bf16 v[18:21], v[106:109], v[218:221], v[18:21]
	s_waitcnt lgkmcnt(5)
	v_mfma_f32_16x16x32_bf16 v[10:13], v[110:113], v[234:237], v[10:13]
	s_waitcnt lgkmcnt(4)
	v_mfma_f32_16x16x32_bf16 v[18:21], v[110:113], v[238:241], v[18:21]
	s_waitcnt lgkmcnt(3)
	v_mfma_f32_16x16x32_bf16 v[30:33], v[106:109], v[242:245], v[30:33]
	s_waitcnt lgkmcnt(2)
	v_mfma_f32_16x16x32_bf16 v[34:37], v[106:109], v[246:249], v[34:37]
	s_waitcnt lgkmcnt(1)
	v_mfma_f32_16x16x32_bf16 v[30:33], v[110:113], v[250:253], v[30:33]
	v_lshlrev_b32_e32 v106, 1, v159
	v_add3_u32 v4, 0, v4, v106
	s_waitcnt lgkmcnt(0)
	v_mfma_f32_16x16x32_bf16 v[34:37], v[110:113], v[114:117], v[34:37]
	ds_read_b128 v[118:121], v4 offset:50176
	ds_read_b128 v[106:109], v4 offset:50192
	v_lshl_add_u32 v4, v159, 2, 0
	v_add_u32_e32 v4, 0x20840, v4
	ds_read_b128 v[126:129], v4
	ds_read_b128 v[122:125], v4 offset:16
	ds_read_b128 v[114:117], v4 offset:32
	ds_read_b128 v[110:113], v4 offset:48
	v_ashrrev_i32_e32 v4, 2, v191
	v_mul_lo_u32 v146, v4, s63
	v_add3_u32 v151, s18, v146, v147
	ds_read_b128 v[146:149], v151
	ds_read_b128 v[160:163], v151 offset:16
	v_lshl_add_u32 v151, v150, 6, 0
	v_add_u32_e32 v151, 0x20200, v151
	ds_read_b128 v[164:167], v151
	ds_read_b128 v[196:199], v151 offset:16
	ds_read_b128 v[200:203], v151 offset:32
	ds_read_b128 v[204:207], v151 offset:48
	s_waitcnt lgkmcnt(5)
	v_lshlrev_b32_e32 v151, 16, v146
	v_and_b32_e32 v146, 0xffff0000, v146
	s_waitcnt lgkmcnt(3)
	v_mul_f32_e32 v146, v165, v146
	v_fmac_f32_e32 v146, v164, v151
	v_lshlrev_b32_e32 v151, 16, v147
	v_fmac_f32_e32 v146, v166, v151
	v_and_b32_e32 v147, 0xffff0000, v147
	v_fmac_f32_e32 v146, v167, v147
	v_lshlrev_b32_e32 v147, 16, v148
	s_waitcnt lgkmcnt(2)
	v_fmac_f32_e32 v146, v196, v147
	v_and_b32_e32 v147, 0xffff0000, v148
	v_fmac_f32_e32 v146, v197, v147
	v_lshlrev_b32_e32 v147, 16, v149
	v_fmac_f32_e32 v146, v198, v147
	v_and_b32_e32 v147, 0xffff0000, v149
	v_fmac_f32_e32 v146, v199, v147
	v_lshlrev_b32_e32 v147, 16, v160
	s_waitcnt lgkmcnt(1)
	v_fmac_f32_e32 v146, v200, v147
	v_and_b32_e32 v147, 0xffff0000, v160
	v_fmac_f32_e32 v146, v201, v147
	v_lshlrev_b32_e32 v147, 16, v161
	v_fmac_f32_e32 v146, v202, v147
	v_and_b32_e32 v147, 0xffff0000, v161
	v_fmac_f32_e32 v146, v203, v147
	v_lshlrev_b32_e32 v147, 16, v162
	s_waitcnt lgkmcnt(0)
	v_fmac_f32_e32 v146, v204, v147
	v_and_b32_e32 v147, 0xffff0000, v162
	v_fmac_f32_e32 v146, v205, v147
	v_lshlrev_b32_e32 v147, 16, v163
	v_fmac_f32_e32 v146, v206, v147
	v_and_b32_e32 v147, 0xffff0000, v163
	v_fmac_f32_e32 v146, v207, v147
	s_nop 1
	v_add_f32_dpp v146, v146, v146 quad_perm:[1,0,3,2] row_mask:0xf bank_mask:0xf bound_ctrl:1
	s_nop 1
	v_mov_b32_dpp v147, v146 quad_perm:[2,3,0,1] row_mask:0xf bank_mask:0xf bound_ctrl:1
	s_and_saveexec_b64 s[16:17], vcc
	s_cbranch_execz .LBB0_377
	v_lshl_add_u32 v4, v4, 2, 0
	v_add_f32_e32 v146, v146, v147
	v_add_u32_e32 v147, 0x20840, v4
	ds_read_b32 v147, v147
	v_add_u32_e32 v4, 0x20e80, v4
	s_waitcnt lgkmcnt(0)
	v_fmac_f32_e32 v146, v182, v147
	ds_write_b32 v4, v146
